# remove 18 compiler-duplicated lgkmcnt(0) waits at MFMA phase heads in the three GEMM loops
# speedup vs baseline: 1.0113x; 1.0068x over previous
.LBB0_254:
	s_add_u32 s2, s20, 0xfffc0080
	s_addc_u32 s3, s21, -1
	s_add_i32 s70, 0, 0x10000
	v_add_u32_e32 v0, s70, v143
	ds_read_b128 v[156:159], v0
	ds_read_b128 v[170:173], v0 offset:1024
	ds_read_b128 v[174:177], v0 offset:2048
	ds_read_b128 v[178:181], v0 offset:3072
	s_cmp_eq_u32 s69, 12
	s_cselect_b32 s29, s31, s3
	s_cselect_b32 s28, s65, s2
	s_cselect_b32 s3, s1, s68
	s_cselect_b32 s2, s66, s67
	v_lshl_add_u64 v[130:131], s[20:21], 0, v[152:153]
	s_add_i32 m0, s33, 0xc000
	ds_read_b128 v[182:185], v169
	ds_read_b128 v[186:189], v169 offset:1024
	ds_read_b128 v[190:193], v169 offset:2048
	ds_read_b128 v[194:197], v169 offset:3072
	ds_read_b128 v[198:201], v169 offset:4096
	ds_read_b128 v[202:205], v169 offset:5120
	ds_read_b128 v[206:209], v169 offset:6144
	ds_read_b128 v[210:213], v169 offset:7168
	global_load_lds_dwordx4 v[130:131], off
	v_lshl_add_u64 v[130:131], s[20:21], 0, v[154:155]
	s_add_i32 m0, s33, 0xe000
	s_nop 0
	global_load_lds_dwordx4 v[130:131], off
	s_waitcnt lgkmcnt(8)
	s_barrier
	s_waitcnt lgkmcnt(0)
	s_setprio 1
	v_mfma_f32_16x16x32_bf16 v[126:129], v[156:159], v[182:185], v[126:129]
	v_mfma_f32_16x16x32_bf16 v[122:125], v[174:177], v[182:185], v[122:125]
	v_mfma_f32_16x16x32_bf16 v[110:113], v[156:159], v[190:193], v[110:113]
	v_mfma_f32_16x16x32_bf16 v[106:109], v[174:177], v[190:193], v[106:109]
	v_mfma_f32_16x16x32_bf16 v[94:97], v[156:159], v[198:201], v[94:97]
	v_mfma_f32_16x16x32_bf16 v[90:93], v[174:177], v[198:201], v[90:93]
	v_mfma_f32_16x16x32_bf16 v[78:81], v[156:159], v[206:209], v[78:81]
	v_mfma_f32_16x16x32_bf16 v[74:77], v[174:177], v[206:209], v[74:77]
	v_mfma_f32_16x16x32_bf16 v[126:129], v[170:173], v[186:189], v[126:129]
	v_mfma_f32_16x16x32_bf16 v[122:125], v[178:181], v[186:189], v[122:125]
	v_mfma_f32_16x16x32_bf16 v[110:113], v[170:173], v[194:197], v[110:113]
	v_mfma_f32_16x16x32_bf16 v[106:109], v[178:181], v[194:197], v[106:109]
	v_mfma_f32_16x16x32_bf16 v[94:97], v[170:173], v[202:205], v[94:97]
	v_mfma_f32_16x16x32_bf16 v[90:93], v[178:181], v[202:205], v[90:93]
	v_mfma_f32_16x16x32_bf16 v[78:81], v[170:173], v[210:213], v[78:81]
	v_mfma_f32_16x16x32_bf16 v[74:77], v[178:181], v[210:213], v[74:77]
	s_setprio 0
	s_barrier
	s_add_i32 s72, 0, 0x14000
	s_add_i32 s70, s70, s23
	v_add_u32_e32 v0, s72, v143
	v_lshl_add_u64 v[130:131], s[2:3], 0, v[148:149]
	s_mov_b32 m0, s70
	ds_read_b128 v[214:217], v0
	ds_read_b128 v[218:221], v0 offset:1024
	ds_read_b128 v[222:225], v0 offset:2048
	ds_read_b128 v[226:229], v0 offset:3072
	global_load_lds_dwordx4 v[130:131], off
	v_lshl_add_u64 v[132:133], s[2:3], 0, v[144:145]
	s_add_i32 m0, s70, 0x2000
	s_nop 0
	global_load_lds_dwordx4 v[132:133], off
	s_barrier
	s_waitcnt lgkmcnt(0)
	s_setprio 1
	v_mfma_f32_16x16x32_bf16 v[118:121], v[214:217], v[182:185], v[118:121]
	v_mfma_f32_16x16x32_bf16 v[114:117], v[222:225], v[182:185], v[114:117]
	v_mfma_f32_16x16x32_bf16 v[102:105], v[214:217], v[190:193], v[102:105]
	v_mfma_f32_16x16x32_bf16 v[98:101], v[222:225], v[190:193], v[98:101]
	v_mfma_f32_16x16x32_bf16 v[86:89], v[214:217], v[198:201], v[86:89]
	v_mfma_f32_16x16x32_bf16 v[82:85], v[222:225], v[198:201], v[82:85]
	v_mfma_f32_16x16x32_bf16 v[70:73], v[214:217], v[206:209], v[70:73]
	v_mfma_f32_16x16x32_bf16 v[66:69], v[222:225], v[206:209], v[66:69]
	v_mfma_f32_16x16x32_bf16 v[118:121], v[218:221], v[186:189], v[118:121]
	v_mfma_f32_16x16x32_bf16 v[114:117], v[226:229], v[186:189], v[114:117]
	v_mfma_f32_16x16x32_bf16 v[102:105], v[218:221], v[194:197], v[102:105]
	v_mfma_f32_16x16x32_bf16 v[98:101], v[226:229], v[194:197], v[98:101]
	v_mfma_f32_16x16x32_bf16 v[86:89], v[218:221], v[202:205], v[86:89]
	v_mfma_f32_16x16x32_bf16 v[82:85], v[226:229], v[202:205], v[82:85]
	v_mfma_f32_16x16x32_bf16 v[70:73], v[218:221], v[210:213], v[70:73]
	v_mfma_f32_16x16x32_bf16 v[66:69], v[226:229], v[210:213], v[66:69]
	s_setprio 0
	s_mov_b32 m0, s33
	v_lshl_add_u64 v[162:163], s[28:29], 0, v[150:151]
	s_barrier
	ds_read_b128 v[182:185], v169 offset:16384
	ds_read_b128 v[186:189], v169 offset:17408
	ds_read_b128 v[190:193], v169 offset:18432
	ds_read_b128 v[194:197], v169 offset:19456
	ds_read_b128 v[198:201], v169 offset:20480
	ds_read_b128 v[202:205], v169 offset:21504
	ds_read_b128 v[206:209], v169 offset:22528
	ds_read_b128 v[210:213], v169 offset:23552
	global_load_lds_dwordx4 v[162:163], off
	v_lshl_add_u64 v[164:165], s[28:29], 0, v[146:147]
	s_mov_b32 m0, s35
	s_nop 0
	global_load_lds_dwordx4 v[164:165], off
	s_barrier
	s_waitcnt lgkmcnt(0)
	s_setprio 1
	v_mfma_f32_16x16x32_bf16 v[62:65], v[156:159], v[182:185], v[62:65]
	v_mfma_f32_16x16x32_bf16 v[58:61], v[174:177], v[182:185], v[58:61]
	v_mfma_f32_16x16x32_bf16 v[50:53], v[156:159], v[190:193], v[50:53]
	v_mfma_f32_16x16x32_bf16 v[42:45], v[174:177], v[190:193], v[42:45]
	v_mfma_f32_16x16x32_bf16 v[34:37], v[156:159], v[198:201], v[34:37]
	v_mfma_f32_16x16x32_bf16 v[26:29], v[174:177], v[198:201], v[26:29]
	v_mfma_f32_16x16x32_bf16 v[18:21], v[156:159], v[206:209], v[18:21]
	v_mfma_f32_16x16x32_bf16 v[10:13], v[174:177], v[206:209], v[10:13]
	v_mfma_f32_16x16x32_bf16 v[62:65], v[170:173], v[186:189], v[62:65]
	v_mfma_f32_16x16x32_bf16 v[58:61], v[178:181], v[186:189], v[58:61]
	v_mfma_f32_16x16x32_bf16 v[50:53], v[170:173], v[194:197], v[50:53]
	v_mfma_f32_16x16x32_bf16 v[42:45], v[178:181], v[194:197], v[42:45]
	v_mfma_f32_16x16x32_bf16 v[34:37], v[170:173], v[202:205], v[34:37]
	v_mfma_f32_16x16x32_bf16 v[26:29], v[178:181], v[202:205], v[26:29]
	v_mfma_f32_16x16x32_bf16 v[18:21], v[170:173], v[210:213], v[18:21]
	v_mfma_f32_16x16x32_bf16 v[10:13], v[178:181], v[210:213], v[10:13]
	s_setprio 0
	s_barrier
	s_add_u32 s70, s2, 0x40000
	s_addc_u32 s71, s3, 0
	s_add_i32 s72, s72, s23
	v_lshl_add_u64 v[156:157], s[70:71], 0, v[148:149]
	s_mov_b32 m0, s72
	s_nop 0
	global_load_lds_dwordx4 v[156:157], off
	v_lshl_add_u64 v[156:157], s[70:71], 0, v[144:145]
	s_add_i32 m0, s72, 0x2000
	s_nop 0
	global_load_lds_dwordx4 v[156:157], off
	s_waitcnt vmcnt(6)
	s_barrier
	s_setprio 1
	v_mfma_f32_16x16x32_bf16 v[54:57], v[214:217], v[182:185], v[54:57]
	v_mfma_f32_16x16x32_bf16 v[46:49], v[222:225], v[182:185], v[46:49]
	v_mfma_f32_16x16x32_bf16 v[38:41], v[214:217], v[190:193], v[38:41]
	v_mfma_f32_16x16x32_bf16 v[30:33], v[222:225], v[190:193], v[30:33]
	v_mfma_f32_16x16x32_bf16 v[22:25], v[214:217], v[198:201], v[22:25]
	v_mfma_f32_16x16x32_bf16 v[14:17], v[222:225], v[198:201], v[14:17]
	v_mfma_f32_16x16x32_bf16 v[6:9], v[214:217], v[206:209], v[6:9]
	v_mfma_f32_16x16x32_bf16 v[2:5], v[222:225], v[206:209], v[2:5]
	v_mfma_f32_16x16x32_bf16 v[54:57], v[218:221], v[186:189], v[54:57]
	v_mfma_f32_16x16x32_bf16 v[46:49], v[226:229], v[186:189], v[46:49]
	v_mfma_f32_16x16x32_bf16 v[38:41], v[218:221], v[194:197], v[38:41]
	v_mfma_f32_16x16x32_bf16 v[30:33], v[226:229], v[194:197], v[30:33]
	v_mfma_f32_16x16x32_bf16 v[22:25], v[218:221], v[202:205], v[22:25]
	v_mfma_f32_16x16x32_bf16 v[14:17], v[226:229], v[202:205], v[14:17]
	v_mfma_f32_16x16x32_bf16 v[6:9], v[218:221], v[210:213], v[6:9]
	v_mfma_f32_16x16x32_bf16 v[2:5], v[226:229], v[210:213], v[2:5]
	s_setprio 0
	s_add_i32 s70, 0, 0x18000
	v_add_u32_e32 v0, s70, v143
	s_barrier
	ds_read_b128 v[156:159], v0
	ds_read_b128 v[170:173], v0 offset:1024
	ds_read_b128 v[174:177], v0 offset:2048
	ds_read_b128 v[178:181], v0 offset:3072
	s_add_u32 s28, s28, 0x40000
	s_addc_u32 s29, s29, 0
	s_mov_b32 m0, s41
	v_lshl_add_u64 v[214:215], s[28:29], 0, v[150:151]
	ds_read_b128 v[182:185], v169 offset:32768
	ds_read_b128 v[186:189], v169 offset:33792
	ds_read_b128 v[190:193], v169 offset:34816
	ds_read_b128 v[194:197], v169 offset:35840
	ds_read_b128 v[198:201], v169 offset:36864
	ds_read_b128 v[202:205], v169 offset:37888
	ds_read_b128 v[206:209], v169 offset:38912
	ds_read_b128 v[210:213], v169 offset:39936
	global_load_lds_dwordx4 v[214:215], off
	v_lshl_add_u64 v[214:215], s[28:29], 0, v[146:147]
	s_mov_b32 m0, s44
	s_nop 0
	global_load_lds_dwordx4 v[214:215], off
	s_waitcnt lgkmcnt(8)
	s_barrier
	s_waitcnt lgkmcnt(0)
	s_setprio 1
	v_mfma_f32_16x16x32_bf16 v[126:129], v[156:159], v[182:185], v[126:129]
	v_mfma_f32_16x16x32_bf16 v[122:125], v[174:177], v[182:185], v[122:125]
	v_mfma_f32_16x16x32_bf16 v[110:113], v[156:159], v[190:193], v[110:113]
	v_mfma_f32_16x16x32_bf16 v[106:109], v[174:177], v[190:193], v[106:109]
	v_mfma_f32_16x16x32_bf16 v[94:97], v[156:159], v[198:201], v[94:97]
	v_mfma_f32_16x16x32_bf16 v[90:93], v[174:177], v[198:201], v[90:93]
	v_mfma_f32_16x16x32_bf16 v[78:81], v[156:159], v[206:209], v[78:81]
	v_mfma_f32_16x16x32_bf16 v[74:77], v[174:177], v[206:209], v[74:77]
	v_mfma_f32_16x16x32_bf16 v[126:129], v[170:173], v[186:189], v[126:129]
	v_mfma_f32_16x16x32_bf16 v[122:125], v[178:181], v[186:189], v[122:125]
	v_mfma_f32_16x16x32_bf16 v[110:113], v[170:173], v[194:197], v[110:113]
	v_mfma_f32_16x16x32_bf16 v[106:109], v[178:181], v[194:197], v[106:109]
	v_mfma_f32_16x16x32_bf16 v[94:97], v[170:173], v[202:205], v[94:97]
	v_mfma_f32_16x16x32_bf16 v[90:93], v[178:181], v[202:205], v[90:93]
	v_mfma_f32_16x16x32_bf16 v[78:81], v[170:173], v[210:213], v[78:81]
	v_mfma_f32_16x16x32_bf16 v[74:77], v[178:181], v[210:213], v[74:77]
	s_setprio 0
	s_barrier
	s_add_i32 s28, 0, 0x1c000
	s_add_i32 s29, s70, s23
	v_add_u32_e32 v0, s28, v143
	v_lshl_add_u64 v[130:131], v[130:131], 0, s[26:27]
	s_mov_b32 m0, s29
	ds_read_b128 v[214:217], v0
	ds_read_b128 v[218:221], v0 offset:1024
	ds_read_b128 v[222:225], v0 offset:2048
	ds_read_b128 v[226:229], v0 offset:3072
	global_load_lds_dwordx4 v[130:131], off
	v_lshl_add_u64 v[130:131], v[132:133], 0, s[26:27]
	s_add_i32 m0, s29, 0x2000
	s_nop 0
	global_load_lds_dwordx4 v[130:131], off
	s_barrier
	s_waitcnt lgkmcnt(0)
	s_setprio 1
	v_mfma_f32_16x16x32_bf16 v[118:121], v[214:217], v[182:185], v[118:121]
	v_mfma_f32_16x16x32_bf16 v[114:117], v[222:225], v[182:185], v[114:117]
	v_mfma_f32_16x16x32_bf16 v[102:105], v[214:217], v[190:193], v[102:105]
	v_mfma_f32_16x16x32_bf16 v[98:101], v[222:225], v[190:193], v[98:101]
	v_mfma_f32_16x16x32_bf16 v[86:89], v[214:217], v[198:201], v[86:89]
	v_mfma_f32_16x16x32_bf16 v[82:85], v[222:225], v[198:201], v[82:85]
	v_mfma_f32_16x16x32_bf16 v[70:73], v[214:217], v[206:209], v[70:73]
	v_mfma_f32_16x16x32_bf16 v[66:69], v[222:225], v[206:209], v[66:69]
	v_mfma_f32_16x16x32_bf16 v[118:121], v[218:221], v[186:189], v[118:121]
	v_mfma_f32_16x16x32_bf16 v[114:117], v[226:229], v[186:189], v[114:117]
	v_mfma_f32_16x16x32_bf16 v[102:105], v[218:221], v[194:197], v[102:105]
	v_mfma_f32_16x16x32_bf16 v[98:101], v[226:229], v[194:197], v[98:101]
	v_mfma_f32_16x16x32_bf16 v[86:89], v[218:221], v[202:205], v[86:89]
	v_mfma_f32_16x16x32_bf16 v[82:85], v[226:229], v[202:205], v[82:85]
	v_mfma_f32_16x16x32_bf16 v[70:73], v[218:221], v[210:213], v[70:73]
	v_mfma_f32_16x16x32_bf16 v[66:69], v[226:229], v[210:213], v[66:69]
	s_setprio 0
	s_mov_b32 m0, s40
	v_lshl_add_u64 v[130:131], v[162:163], 0, s[26:27]
	s_barrier
	ds_read_b128 v[182:185], v169 offset:49152
	ds_read_b128 v[186:189], v169 offset:50176
	ds_read_b128 v[190:193], v169 offset:51200
	ds_read_b128 v[194:197], v169 offset:52224
	ds_read_b128 v[198:201], v169 offset:53248
	ds_read_b128 v[202:205], v169 offset:54272
	ds_read_b128 v[206:209], v169 offset:55296
	ds_read_b128 v[210:213], v169 offset:56320
	global_load_lds_dwordx4 v[130:131], off
	v_lshl_add_u64 v[130:131], v[164:165], 0, s[26:27]
	s_mov_b32 m0, s45
	s_nop 0
	global_load_lds_dwordx4 v[130:131], off
	s_barrier
	s_waitcnt lgkmcnt(0)
	s_setprio 1
	v_mfma_f32_16x16x32_bf16 v[62:65], v[156:159], v[182:185], v[62:65]
	v_mfma_f32_16x16x32_bf16 v[58:61], v[174:177], v[182:185], v[58:61]
	v_mfma_f32_16x16x32_bf16 v[50:53], v[156:159], v[190:193], v[50:53]
	v_mfma_f32_16x16x32_bf16 v[42:45], v[174:177], v[190:193], v[42:45]
	v_mfma_f32_16x16x32_bf16 v[34:37], v[156:159], v[198:201], v[34:37]
	v_mfma_f32_16x16x32_bf16 v[26:29], v[174:177], v[198:201], v[26:29]
	v_mfma_f32_16x16x32_bf16 v[18:21], v[156:159], v[206:209], v[18:21]
	v_mfma_f32_16x16x32_bf16 v[10:13], v[174:177], v[206:209], v[10:13]
	v_mfma_f32_16x16x32_bf16 v[62:65], v[170:173], v[186:189], v[62:65]
	v_mfma_f32_16x16x32_bf16 v[58:61], v[178:181], v[186:189], v[58:61]
	v_mfma_f32_16x16x32_bf16 v[50:53], v[170:173], v[194:197], v[50:53]
	v_mfma_f32_16x16x32_bf16 v[42:45], v[178:181], v[194:197], v[42:45]
	v_mfma_f32_16x16x32_bf16 v[34:37], v[170:173], v[202:205], v[34:37]
	v_mfma_f32_16x16x32_bf16 v[26:29], v[178:181], v[202:205], v[26:29]
	v_mfma_f32_16x16x32_bf16 v[18:21], v[170:173], v[210:213], v[18:21]
	v_mfma_f32_16x16x32_bf16 v[10:13], v[178:181], v[210:213], v[10:13]
	s_setprio 0
	s_barrier
	s_add_u32 s2, s2, 0x40080
	s_addc_u32 s3, s3, 0
	s_add_i32 s28, s28, s23
	v_lshl_add_u64 v[130:131], s[2:3], 0, v[148:149]
	s_mov_b32 m0, s28
	s_nop 0
	global_load_lds_dwordx4 v[130:131], off
	v_lshl_add_u64 v[130:131], s[2:3], 0, v[144:145]
	s_add_i32 m0, s28, 0x2000
	s_nop 0
	global_load_lds_dwordx4 v[130:131], off
	s_waitcnt vmcnt(6)
	s_barrier
	s_setprio 1
	v_mfma_f32_16x16x32_bf16 v[54:57], v[214:217], v[182:185], v[54:57]
	v_mfma_f32_16x16x32_bf16 v[46:49], v[222:225], v[182:185], v[46:49]
	v_mfma_f32_16x16x32_bf16 v[38:41], v[214:217], v[190:193], v[38:41]
	v_mfma_f32_16x16x32_bf16 v[30:33], v[222:225], v[190:193], v[30:33]
	v_mfma_f32_16x16x32_bf16 v[22:25], v[214:217], v[198:201], v[22:25]
	v_mfma_f32_16x16x32_bf16 v[14:17], v[222:225], v[198:201], v[14:17]
	v_mfma_f32_16x16x32_bf16 v[6:9], v[214:217], v[206:209], v[6:9]
	v_mfma_f32_16x16x32_bf16 v[2:5], v[222:225], v[206:209], v[2:5]
	v_mfma_f32_16x16x32_bf16 v[54:57], v[218:221], v[186:189], v[54:57]
	v_mfma_f32_16x16x32_bf16 v[46:49], v[226:229], v[186:189], v[46:49]
	v_mfma_f32_16x16x32_bf16 v[38:41], v[218:221], v[194:197], v[38:41]
	v_mfma_f32_16x16x32_bf16 v[30:33], v[226:229], v[194:197], v[30:33]
	v_mfma_f32_16x16x32_bf16 v[22:25], v[218:221], v[202:205], v[22:25]
	v_mfma_f32_16x16x32_bf16 v[14:17], v[226:229], v[202:205], v[14:17]
	v_mfma_f32_16x16x32_bf16 v[6:9], v[218:221], v[210:213], v[6:9]
	v_mfma_f32_16x16x32_bf16 v[2:5], v[226:229], v[210:213], v[2:5]
	s_setprio 0
	s_add_i32 s69, s69, 2
	s_add_u32 s20, s20, 0x100
	s_addc_u32 s21, s21, 0
	s_add_u32 s67, s67, 0x100
	s_addc_u32 s68, s68, 0
	s_cmp_gt_u32 s69, 13
	s_barrier
	s_cbranch_scc0 .LBB0_254
	s_add_i32 s1, s47, -4
	v_readlane_b32 s20, v251, 20
	v_lshl_add_u32 v156, s64, 8, v141
	s_cmp_gt_u32 s1, 7
	s_mov_b64 s[2:3], -1
	v_readlane_b32 s21, v251, 21
	s_cbranch_scc0 .LBB0_261
	s_mov_b64 s[2:3], 0
	s_cmp_lt_i32 s47, 4
	s_mov_b32 s1, s47
	s_cbranch_scc1 .LBB0_260
	s_add_i32 s1, s47, -12
	s_cmp_lt_u32 s1, 4
	s_mov_b64 s[2:3], 0x30c0000
	s_cbranch_scc1 .LBB0_259
	s_lshr_b32 s1, s1, 2
	s_add_i32 s2, s1, 2
	s_cmp_lg_u32 s1, 1
	s_cselect_b32 s1, s2, 1
	s_mul_hi_u32 s3, s1, 0x1040000
	s_mul_i32 s2, s1, 0x1040000

.LBB0_318:
	s_add_i32 s71, s2, 2
	s_add_u32 s98, vcc_lo, 0x80
	s_addc_u32 s3, vcc_hi, 0
	s_add_i32 s73, 0, 0x10000
	v_add_u32_e32 v0, s73, v143
	ds_read_b128 v[168:171], v0
	ds_read_b128 v[172:175], v0 offset:1024
	ds_read_b128 v[176:179], v0 offset:2048
	ds_read_b128 v[180:183], v0 offset:3072
	s_cmp_eq_u32 s22, s2
	s_cselect_b32 s2, s20, s98
	s_cselect_b32 s3, s21, s3
	s_cselect_b32 s99, s1, s47
	s_cselect_b32 s98, s0, s23
	v_lshl_add_u64 v[130:131], vcc, 0, v[152:153]
	s_add_i32 m0, s43, 0xc000
	ds_read_b128 v[184:187], v159
	ds_read_b128 v[188:191], v159 offset:1024
	ds_read_b128 v[192:195], v159 offset:2048
	ds_read_b128 v[196:199], v159 offset:3072
	ds_read_b128 v[200:203], v159 offset:4096
	ds_read_b128 v[204:207], v159 offset:5120
	ds_read_b128 v[208:211], v159 offset:6144
	ds_read_b128 v[212:215], v159 offset:7168
	global_load_lds_dwordx4 v[130:131], off
	v_lshl_add_u64 v[130:131], vcc, 0, v[154:155]
	s_add_i32 m0, s43, 0xe000
	s_nop 0
	global_load_lds_dwordx4 v[130:131], off
	s_waitcnt lgkmcnt(8)
	s_barrier
	s_waitcnt lgkmcnt(0)
	s_setprio 1
	v_mfma_f32_16x16x32_bf16 v[126:129], v[168:171], v[184:187], v[126:129]
	v_mfma_f32_16x16x32_bf16 v[122:125], v[176:179], v[184:187], v[122:125]
	v_mfma_f32_16x16x32_bf16 v[118:121], v[168:171], v[192:195], v[118:121]
	v_mfma_f32_16x16x32_bf16 v[110:113], v[176:179], v[192:195], v[110:113]
	v_mfma_f32_16x16x32_bf16 v[102:105], v[168:171], v[200:203], v[102:105]
	v_mfma_f32_16x16x32_bf16 v[94:97], v[176:179], v[200:203], v[94:97]
	v_mfma_f32_16x16x32_bf16 v[86:89], v[168:171], v[208:211], v[86:89]
	v_mfma_f32_16x16x32_bf16 v[78:81], v[176:179], v[208:211], v[78:81]
	v_mfma_f32_16x16x32_bf16 v[126:129], v[172:175], v[188:191], v[126:129]
	v_mfma_f32_16x16x32_bf16 v[122:125], v[180:183], v[188:191], v[122:125]
	v_mfma_f32_16x16x32_bf16 v[118:121], v[172:175], v[196:199], v[118:121]
	v_mfma_f32_16x16x32_bf16 v[110:113], v[180:183], v[196:199], v[110:113]
	v_mfma_f32_16x16x32_bf16 v[102:105], v[172:175], v[204:207], v[102:105]
	v_mfma_f32_16x16x32_bf16 v[94:97], v[180:183], v[204:207], v[94:97]
	v_mfma_f32_16x16x32_bf16 v[86:89], v[172:175], v[212:215], v[86:89]
	v_mfma_f32_16x16x32_bf16 v[78:81], v[180:183], v[212:215], v[78:81]
	s_setprio 0
	s_barrier
	s_add_i32 s70, 0, 0x14000
	s_add_i32 s73, s73, s41
	v_add_u32_e32 v0, s70, v143
	v_lshl_add_u64 v[130:131], s[98:99], 0, v[146:147]
	s_mov_b32 m0, s73
	ds_read_b128 v[216:219], v0
	ds_read_b128 v[220:223], v0 offset:1024
	ds_read_b128 v[224:227], v0 offset:2048
	ds_read_b128 v[228:231], v0 offset:3072
	global_load_lds_dwordx4 v[130:131], off
	v_lshl_add_u64 v[132:133], s[98:99], 0, v[150:151]
	s_add_i32 m0, s73, 0x2000
	s_nop 0
	global_load_lds_dwordx4 v[132:133], off
	s_barrier
	s_waitcnt lgkmcnt(0)
	s_setprio 1
	v_mfma_f32_16x16x32_bf16 v[114:117], v[216:219], v[184:187], v[114:117]
	v_mfma_f32_16x16x32_bf16 v[106:109], v[224:227], v[184:187], v[106:109]
	v_mfma_f32_16x16x32_bf16 v[98:101], v[216:219], v[192:195], v[98:101]
	v_mfma_f32_16x16x32_bf16 v[90:93], v[224:227], v[192:195], v[90:93]
	v_mfma_f32_16x16x32_bf16 v[82:85], v[216:219], v[200:203], v[82:85]
	v_mfma_f32_16x16x32_bf16 v[74:77], v[224:227], v[200:203], v[74:77]
	v_mfma_f32_16x16x32_bf16 v[70:73], v[216:219], v[208:211], v[70:73]
	v_mfma_f32_16x16x32_bf16 v[66:69], v[224:227], v[208:211], v[66:69]
	v_mfma_f32_16x16x32_bf16 v[114:117], v[220:223], v[188:191], v[114:117]
	v_mfma_f32_16x16x32_bf16 v[106:109], v[228:231], v[188:191], v[106:109]
	v_mfma_f32_16x16x32_bf16 v[98:101], v[220:223], v[196:199], v[98:101]
	v_mfma_f32_16x16x32_bf16 v[90:93], v[228:231], v[196:199], v[90:93]
	v_mfma_f32_16x16x32_bf16 v[82:85], v[220:223], v[204:207], v[82:85]
	v_mfma_f32_16x16x32_bf16 v[74:77], v[228:231], v[204:207], v[74:77]
	v_mfma_f32_16x16x32_bf16 v[70:73], v[220:223], v[212:215], v[70:73]
	v_mfma_f32_16x16x32_bf16 v[66:69], v[228:231], v[212:215], v[66:69]
	s_setprio 0
	s_mov_b32 m0, s43
	v_lshl_add_u64 v[156:157], s[2:3], 0, v[144:145]
	s_barrier
	ds_read_b128 v[184:187], v159 offset:16384
	ds_read_b128 v[188:191], v159 offset:17408
	ds_read_b128 v[192:195], v159 offset:18432
	ds_read_b128 v[196:199], v159 offset:19456
	ds_read_b128 v[200:203], v159 offset:20480
	ds_read_b128 v[204:207], v159 offset:21504
	ds_read_b128 v[208:211], v159 offset:22528
	ds_read_b128 v[212:215], v159 offset:23552
	global_load_lds_dwordx4 v[156:157], off
	v_lshl_add_u64 v[162:163], s[2:3], 0, v[148:149]
	s_mov_b32 m0, s44
	s_nop 0
	global_load_lds_dwordx4 v[162:163], off
	s_barrier
	s_waitcnt lgkmcnt(0)
	s_setprio 1
	v_mfma_f32_16x16x32_bf16 v[62:65], v[168:171], v[184:187], v[62:65]
	v_mfma_f32_16x16x32_bf16 v[58:61], v[176:179], v[184:187], v[58:61]
	v_mfma_f32_16x16x32_bf16 v[54:57], v[168:171], v[192:195], v[54:57]
	v_mfma_f32_16x16x32_bf16 v[46:49], v[176:179], v[192:195], v[46:49]
	v_mfma_f32_16x16x32_bf16 v[38:41], v[168:171], v[200:203], v[38:41]
	v_mfma_f32_16x16x32_bf16 v[30:33], v[176:179], v[200:203], v[30:33]
	v_mfma_f32_16x16x32_bf16 v[22:25], v[168:171], v[208:211], v[22:25]
	v_mfma_f32_16x16x32_bf16 v[14:17], v[176:179], v[208:211], v[14:17]
	v_mfma_f32_16x16x32_bf16 v[62:65], v[172:175], v[188:191], v[62:65]
	v_mfma_f32_16x16x32_bf16 v[58:61], v[180:183], v[188:191], v[58:61]
	v_mfma_f32_16x16x32_bf16 v[54:57], v[172:175], v[196:199], v[54:57]
	v_mfma_f32_16x16x32_bf16 v[46:49], v[180:183], v[196:199], v[46:49]
	v_mfma_f32_16x16x32_bf16 v[38:41], v[172:175], v[204:207], v[38:41]
	v_mfma_f32_16x16x32_bf16 v[30:33], v[180:183], v[204:207], v[30:33]
	v_mfma_f32_16x16x32_bf16 v[22:25], v[172:175], v[212:215], v[22:25]
	v_mfma_f32_16x16x32_bf16 v[14:17], v[180:183], v[212:215], v[14:17]
	s_setprio 0
	s_barrier
	s_add_u32 s98, s98, s96
	s_addc_u32 s99, s99, 0
	s_add_i32 s70, s70, s41
	v_lshl_add_u64 v[164:165], s[98:99], 0, v[146:147]
	s_mov_b32 m0, s70
	v_lshl_add_u64 v[232:233], s[98:99], 0, v[150:151]
	global_load_lds_dwordx4 v[164:165], off
	s_add_i32 m0, s70, 0x2000
	s_nop 0
	global_load_lds_dwordx4 v[232:233], off
	s_waitcnt vmcnt(6)
	s_barrier
	s_setprio 1
	v_mfma_f32_16x16x32_bf16 v[50:53], v[216:219], v[184:187], v[50:53]
	v_mfma_f32_16x16x32_bf16 v[42:45], v[224:227], v[184:187], v[42:45]
	v_mfma_f32_16x16x32_bf16 v[34:37], v[216:219], v[192:195], v[34:37]
	v_mfma_f32_16x16x32_bf16 v[26:29], v[224:227], v[192:195], v[26:29]
	v_mfma_f32_16x16x32_bf16 v[18:21], v[216:219], v[200:203], v[18:21]
	v_mfma_f32_16x16x32_bf16 v[10:13], v[224:227], v[200:203], v[10:13]
	v_mfma_f32_16x16x32_bf16 v[6:9], v[216:219], v[208:211], v[6:9]
	v_mfma_f32_16x16x32_bf16 v[2:5], v[224:227], v[208:211], v[2:5]
	v_mfma_f32_16x16x32_bf16 v[50:53], v[220:223], v[188:191], v[50:53]
	v_mfma_f32_16x16x32_bf16 v[42:45], v[228:231], v[188:191], v[42:45]
	v_mfma_f32_16x16x32_bf16 v[34:37], v[220:223], v[196:199], v[34:37]
	v_mfma_f32_16x16x32_bf16 v[26:29], v[228:231], v[196:199], v[26:29]
	v_mfma_f32_16x16x32_bf16 v[18:21], v[220:223], v[204:207], v[18:21]
	v_mfma_f32_16x16x32_bf16 v[10:13], v[228:231], v[204:207], v[10:13]
	v_mfma_f32_16x16x32_bf16 v[6:9], v[220:223], v[212:215], v[6:9]
	v_mfma_f32_16x16x32_bf16 v[2:5], v[228:231], v[212:215], v[2:5]
	s_setprio 0
	s_add_i32 s70, 0, 0x18000
	v_add_u32_e32 v0, s70, v143
	s_barrier
	ds_read_b128 v[168:171], v0
	ds_read_b128 v[172:175], v0 offset:1024
	ds_read_b128 v[176:179], v0 offset:2048
	ds_read_b128 v[180:183], v0 offset:3072
	s_add_u32 s2, s2, s96
	s_addc_u32 s3, s3, 0
	s_mov_b32 m0, s45
	v_lshl_add_u64 v[216:217], s[2:3], 0, v[144:145]
	ds_read_b128 v[184:187], v159 offset:32768
	ds_read_b128 v[188:191], v159 offset:33792
	ds_read_b128 v[192:195], v159 offset:34816
	ds_read_b128 v[196:199], v159 offset:35840
	ds_read_b128 v[200:203], v159 offset:36864
	ds_read_b128 v[204:207], v159 offset:37888
	ds_read_b128 v[208:211], v159 offset:38912
	ds_read_b128 v[212:215], v159 offset:39936
	global_load_lds_dwordx4 v[216:217], off
	v_lshl_add_u64 v[216:217], s[2:3], 0, v[148:149]
	s_mov_b32 m0, s40
	s_nop 0
	global_load_lds_dwordx4 v[216:217], off
	s_waitcnt lgkmcnt(8)
	s_barrier
	s_waitcnt lgkmcnt(0)
	s_setprio 1
	v_mfma_f32_16x16x32_bf16 v[126:129], v[168:171], v[184:187], v[126:129]
	v_mfma_f32_16x16x32_bf16 v[122:125], v[176:179], v[184:187], v[122:125]
	v_mfma_f32_16x16x32_bf16 v[118:121], v[168:171], v[192:195], v[118:121]
	v_mfma_f32_16x16x32_bf16 v[110:113], v[176:179], v[192:195], v[110:113]
	v_mfma_f32_16x16x32_bf16 v[102:105], v[168:171], v[200:203], v[102:105]
	v_mfma_f32_16x16x32_bf16 v[94:97], v[176:179], v[200:203], v[94:97]
	v_mfma_f32_16x16x32_bf16 v[86:89], v[168:171], v[208:211], v[86:89]
	v_mfma_f32_16x16x32_bf16 v[78:81], v[176:179], v[208:211], v[78:81]
	v_mfma_f32_16x16x32_bf16 v[126:129], v[172:175], v[188:191], v[126:129]
	v_mfma_f32_16x16x32_bf16 v[122:125], v[180:183], v[188:191], v[122:125]
	v_mfma_f32_16x16x32_bf16 v[118:121], v[172:175], v[196:199], v[118:121]
	v_mfma_f32_16x16x32_bf16 v[110:113], v[180:183], v[196:199], v[110:113]
	v_mfma_f32_16x16x32_bf16 v[102:105], v[172:175], v[204:207], v[102:105]
	v_mfma_f32_16x16x32_bf16 v[94:97], v[180:183], v[204:207], v[94:97]
	v_mfma_f32_16x16x32_bf16 v[86:89], v[172:175], v[212:215], v[86:89]
	v_mfma_f32_16x16x32_bf16 v[78:81], v[180:183], v[212:215], v[78:81]
	s_setprio 0
	s_barrier
	s_add_i32 s2, 0, 0x1c000
	s_add_i32 s3, s70, s41
	v_add_u32_e32 v0, s2, v143
	v_lshl_add_u64 v[130:131], v[130:131], 0, s[26:27]
	s_mov_b32 m0, s3
	ds_read_b128 v[216:219], v0
	ds_read_b128 v[220:223], v0 offset:1024
	ds_read_b128 v[224:227], v0 offset:2048
	ds_read_b128 v[228:231], v0 offset:3072
	global_load_lds_dwordx4 v[130:131], off
	v_lshl_add_u64 v[130:131], v[132:133], 0, s[26:27]
	s_add_i32 m0, s3, 0x2000
	s_nop 0
	global_load_lds_dwordx4 v[130:131], off
	s_barrier
	s_waitcnt lgkmcnt(0)
	s_setprio 1
	v_mfma_f32_16x16x32_bf16 v[114:117], v[216:219], v[184:187], v[114:117]
	v_mfma_f32_16x16x32_bf16 v[106:109], v[224:227], v[184:187], v[106:109]
	v_mfma_f32_16x16x32_bf16 v[98:101], v[216:219], v[192:195], v[98:101]
	v_mfma_f32_16x16x32_bf16 v[90:93], v[224:227], v[192:195], v[90:93]
	v_mfma_f32_16x16x32_bf16 v[82:85], v[216:219], v[200:203], v[82:85]
	v_mfma_f32_16x16x32_bf16 v[74:77], v[224:227], v[200:203], v[74:77]
	v_mfma_f32_16x16x32_bf16 v[70:73], v[216:219], v[208:211], v[70:73]
	v_mfma_f32_16x16x32_bf16 v[66:69], v[224:227], v[208:211], v[66:69]
	v_mfma_f32_16x16x32_bf16 v[114:117], v[220:223], v[188:191], v[114:117]
	v_mfma_f32_16x16x32_bf16 v[106:109], v[228:231], v[188:191], v[106:109]
	v_mfma_f32_16x16x32_bf16 v[98:101], v[220:223], v[196:199], v[98:101]
	v_mfma_f32_16x16x32_bf16 v[90:93], v[228:231], v[196:199], v[90:93]
	v_mfma_f32_16x16x32_bf16 v[82:85], v[220:223], v[204:207], v[82:85]
	v_mfma_f32_16x16x32_bf16 v[74:77], v[228:231], v[204:207], v[74:77]
	v_mfma_f32_16x16x32_bf16 v[70:73], v[220:223], v[212:215], v[70:73]
	v_mfma_f32_16x16x32_bf16 v[66:69], v[228:231], v[212:215], v[66:69]
	s_setprio 0
	s_mov_b32 m0, s66
	v_lshl_add_u64 v[130:131], v[156:157], 0, s[26:27]
	s_barrier
	ds_read_b128 v[184:187], v159 offset:49152
	ds_read_b128 v[188:191], v159 offset:50176
	ds_read_b128 v[192:195], v159 offset:51200
	ds_read_b128 v[196:199], v159 offset:52224
	ds_read_b128 v[200:203], v159 offset:53248
	ds_read_b128 v[204:207], v159 offset:54272
	ds_read_b128 v[208:211], v159 offset:55296
	ds_read_b128 v[212:215], v159 offset:56320
	global_load_lds_dwordx4 v[130:131], off
	v_lshl_add_u64 v[130:131], v[162:163], 0, s[26:27]
	s_mov_b32 m0, s67
	s_nop 0
	global_load_lds_dwordx4 v[130:131], off
	s_barrier
	s_waitcnt lgkmcnt(0)
	s_setprio 1
	v_mfma_f32_16x16x32_bf16 v[62:65], v[168:171], v[184:187], v[62:65]
	v_mfma_f32_16x16x32_bf16 v[58:61], v[176:179], v[184:187], v[58:61]
	v_mfma_f32_16x16x32_bf16 v[54:57], v[168:171], v[192:195], v[54:57]
	v_mfma_f32_16x16x32_bf16 v[46:49], v[176:179], v[192:195], v[46:49]
	v_mfma_f32_16x16x32_bf16 v[38:41], v[168:171], v[200:203], v[38:41]
	v_mfma_f32_16x16x32_bf16 v[30:33], v[176:179], v[200:203], v[30:33]
	v_mfma_f32_16x16x32_bf16 v[22:25], v[168:171], v[208:211], v[22:25]
	v_mfma_f32_16x16x32_bf16 v[14:17], v[176:179], v[208:211], v[14:17]
	v_mfma_f32_16x16x32_bf16 v[62:65], v[172:175], v[188:191], v[62:65]
	v_mfma_f32_16x16x32_bf16 v[58:61], v[180:183], v[188:191], v[58:61]
	v_mfma_f32_16x16x32_bf16 v[54:57], v[172:175], v[196:199], v[54:57]
	v_mfma_f32_16x16x32_bf16 v[46:49], v[180:183], v[196:199], v[46:49]
	v_mfma_f32_16x16x32_bf16 v[38:41], v[172:175], v[204:207], v[38:41]
	v_mfma_f32_16x16x32_bf16 v[30:33], v[180:183], v[204:207], v[30:33]
	v_mfma_f32_16x16x32_bf16 v[22:25], v[172:175], v[212:215], v[22:25]
	v_mfma_f32_16x16x32_bf16 v[14:17], v[180:183], v[212:215], v[14:17]
	s_setprio 0
	s_barrier
	s_add_i32 s2, s2, s41
	v_lshl_add_u64 v[130:131], v[164:165], 0, s[26:27]
	s_mov_b32 m0, s2
	s_nop 0
	global_load_lds_dwordx4 v[130:131], off
	v_lshl_add_u64 v[130:131], v[232:233], 0, s[26:27]
	s_add_i32 m0, s2, 0x2000
	s_nop 0
	global_load_lds_dwordx4 v[130:131], off
	s_waitcnt vmcnt(6)
	s_barrier
	s_setprio 1
	v_mfma_f32_16x16x32_bf16 v[50:53], v[216:219], v[184:187], v[50:53]
	v_mfma_f32_16x16x32_bf16 v[42:45], v[224:227], v[184:187], v[42:45]
	v_mfma_f32_16x16x32_bf16 v[34:37], v[216:219], v[192:195], v[34:37]
	v_mfma_f32_16x16x32_bf16 v[26:29], v[224:227], v[192:195], v[26:29]
	v_mfma_f32_16x16x32_bf16 v[18:21], v[216:219], v[200:203], v[18:21]
	v_mfma_f32_16x16x32_bf16 v[10:13], v[224:227], v[200:203], v[10:13]
	v_mfma_f32_16x16x32_bf16 v[6:9], v[216:219], v[208:211], v[6:9]
	v_mfma_f32_16x16x32_bf16 v[2:5], v[224:227], v[208:211], v[2:5]
	v_mfma_f32_16x16x32_bf16 v[50:53], v[220:223], v[188:191], v[50:53]
	v_mfma_f32_16x16x32_bf16 v[42:45], v[228:231], v[188:191], v[42:45]
	v_mfma_f32_16x16x32_bf16 v[34:37], v[220:223], v[196:199], v[34:37]
	v_mfma_f32_16x16x32_bf16 v[26:29], v[228:231], v[196:199], v[26:29]
	v_mfma_f32_16x16x32_bf16 v[18:21], v[220:223], v[204:207], v[18:21]
	v_mfma_f32_16x16x32_bf16 v[10:13], v[228:231], v[204:207], v[10:13]
	v_mfma_f32_16x16x32_bf16 v[6:9], v[220:223], v[212:215], v[6:9]
	v_mfma_f32_16x16x32_bf16 v[2:5], v[228:231], v[212:215], v[2:5]
	s_setprio 0
	s_add_u32 vcc_lo, vcc_lo, 0x100
	s_addc_u32 vcc_hi, vcc_hi, 0
	s_add_u32 s23, s23, 0x100
	s_addc_u32 s47, s47, 0
	s_cmp_ge_u32 s71, s68
	s_mov_b32 s2, s71
	s_barrier
	s_cbranch_scc0 .LBB0_318
	s_cmp_gt_i32 s64, -1
	s_cbranch_scc0 .LBB0_321
	v_lshlrev_b32_e64 v0, v158, s64
	v_add_u32_e32 v130, s42, v0
	v_ashrrev_i32_e32 v131, 31, v130
	v_readlane_b32 s2, v255, 12
	v_lshlrev_b64 v[130:131], 19, v[130:131]
	v_readlane_b32 s3, v255, 13
	s_nop 1
	v_lshl_add_u64 v[156:157], s[2:3], 0, v[130:131]
	s_mov_b32 s2, 0
	s_cbranch_execnz .LBB0_303
	s_branch .LBB0_302

.LBB0_437:
	s_add_u32 s2, s20, 0xfffc0080
	s_addc_u32 s3, s21, -1
	s_add_i32 s68, 0, 0x10000
	v_add_u32_e32 v130, s68, v143
	ds_read_b128 v[168:171], v130
	ds_read_b128 v[172:175], v130 offset:1024
	ds_read_b128 v[176:179], v130 offset:2048
	ds_read_b128 v[180:183], v130 offset:3072
	s_cmp_eq_u32 s67, 12
	s_cselect_b32 s29, s22, s3
	s_cselect_b32 s28, s23, s2
	s_cselect_b32 s3, s37, s66
	s_cselect_b32 s2, s43, s65
	v_lshl_add_u64 v[130:131], s[20:21], 0, v[150:151]
	s_add_i32 m0, s99, 0xc000
	ds_read_b128 v[184:187], v157
	ds_read_b128 v[188:191], v157 offset:1024
	ds_read_b128 v[192:195], v157 offset:2048
	ds_read_b128 v[196:199], v157 offset:3072
	ds_read_b128 v[200:203], v157 offset:4096
	ds_read_b128 v[204:207], v157 offset:5120
	ds_read_b128 v[208:211], v157 offset:6144
	ds_read_b128 v[212:215], v157 offset:7168
	global_load_lds_dwordx4 v[130:131], off
	v_lshl_add_u64 v[130:131], s[20:21], 0, v[152:153]
	s_add_i32 m0, s99, 0xe000
	s_nop 0
	global_load_lds_dwordx4 v[130:131], off
	s_waitcnt lgkmcnt(8)
	s_barrier
	s_waitcnt lgkmcnt(0)
	s_setprio 1
	v_mfma_f32_16x16x32_bf16 v[126:129], v[168:171], v[184:187], v[126:129]
	v_mfma_f32_16x16x32_bf16 v[114:117], v[176:179], v[184:187], v[114:117]
	v_mfma_f32_16x16x32_bf16 v[110:113], v[168:171], v[192:195], v[110:113]
	v_mfma_f32_16x16x32_bf16 v[98:101], v[176:179], v[192:195], v[98:101]
	v_mfma_f32_16x16x32_bf16 v[94:97], v[168:171], v[200:203], v[94:97]
	v_mfma_f32_16x16x32_bf16 v[82:85], v[176:179], v[200:203], v[82:85]
	v_mfma_f32_16x16x32_bf16 v[78:81], v[168:171], v[208:211], v[78:81]
	v_mfma_f32_16x16x32_bf16 v[66:69], v[176:179], v[208:211], v[66:69]
	v_mfma_f32_16x16x32_bf16 v[126:129], v[172:175], v[188:191], v[126:129]
	v_mfma_f32_16x16x32_bf16 v[114:117], v[180:183], v[188:191], v[114:117]
	v_mfma_f32_16x16x32_bf16 v[110:113], v[172:175], v[196:199], v[110:113]
	v_mfma_f32_16x16x32_bf16 v[98:101], v[180:183], v[196:199], v[98:101]
	v_mfma_f32_16x16x32_bf16 v[94:97], v[172:175], v[204:207], v[94:97]
	v_mfma_f32_16x16x32_bf16 v[82:85], v[180:183], v[204:207], v[82:85]
	v_mfma_f32_16x16x32_bf16 v[78:81], v[172:175], v[212:215], v[78:81]
	v_mfma_f32_16x16x32_bf16 v[66:69], v[180:183], v[212:215], v[66:69]
	s_setprio 0
	s_barrier
	s_add_i32 s70, 0, 0x14000
	v_add_u32_e32 v130, s70, v143
	s_add_i32 s68, s68, s98
	ds_read_b128 v[216:219], v130
	ds_read_b128 v[220:223], v130 offset:1024
	ds_read_b128 v[224:227], v130 offset:2048
	ds_read_b128 v[228:231], v130 offset:3072
	v_lshl_add_u64 v[130:131], s[2:3], 0, v[0:1]
	s_mov_b32 m0, s68
	v_lshl_add_u64 v[132:133], s[2:3], 0, v[144:145]
	global_load_lds_dwordx4 v[130:131], off
	s_add_i32 m0, s68, 0x2000
	s_nop 0
	global_load_lds_dwordx4 v[132:133], off
	s_barrier
	s_waitcnt lgkmcnt(0)
	s_setprio 1
	v_mfma_f32_16x16x32_bf16 v[122:125], v[216:219], v[184:187], v[122:125]
	v_mfma_f32_16x16x32_bf16 v[118:121], v[224:227], v[184:187], v[118:121]
	v_mfma_f32_16x16x32_bf16 v[106:109], v[216:219], v[192:195], v[106:109]
	v_mfma_f32_16x16x32_bf16 v[102:105], v[224:227], v[192:195], v[102:105]
	v_mfma_f32_16x16x32_bf16 v[90:93], v[216:219], v[200:203], v[90:93]
	v_mfma_f32_16x16x32_bf16 v[86:89], v[224:227], v[200:203], v[86:89]
	v_mfma_f32_16x16x32_bf16 v[74:77], v[216:219], v[208:211], v[74:77]
	v_mfma_f32_16x16x32_bf16 v[70:73], v[224:227], v[208:211], v[70:73]
	v_mfma_f32_16x16x32_bf16 v[122:125], v[220:223], v[188:191], v[122:125]
	v_mfma_f32_16x16x32_bf16 v[118:121], v[228:231], v[188:191], v[118:121]
	v_mfma_f32_16x16x32_bf16 v[106:109], v[220:223], v[196:199], v[106:109]
	v_mfma_f32_16x16x32_bf16 v[102:105], v[228:231], v[196:199], v[102:105]
	v_mfma_f32_16x16x32_bf16 v[90:93], v[220:223], v[204:207], v[90:93]
	v_mfma_f32_16x16x32_bf16 v[86:89], v[228:231], v[204:207], v[86:89]
	v_mfma_f32_16x16x32_bf16 v[74:77], v[220:223], v[212:215], v[74:77]
	v_mfma_f32_16x16x32_bf16 v[70:73], v[228:231], v[212:215], v[70:73]
	s_setprio 0
	s_mov_b32 m0, s99
	v_lshl_add_u64 v[154:155], s[28:29], 0, v[148:149]
	s_barrier
	ds_read_b128 v[184:187], v157 offset:16384
	ds_read_b128 v[188:191], v157 offset:17408
	ds_read_b128 v[192:195], v157 offset:18432
	ds_read_b128 v[196:199], v157 offset:19456
	ds_read_b128 v[200:203], v157 offset:20480
	ds_read_b128 v[204:207], v157 offset:21504
	ds_read_b128 v[208:211], v157 offset:22528
	ds_read_b128 v[212:215], v157 offset:23552
	global_load_lds_dwordx4 v[154:155], off
	v_lshl_add_u64 v[158:159], s[28:29], 0, v[146:147]
	s_mov_b32 m0, s41
	s_nop 0
	global_load_lds_dwordx4 v[158:159], off
	s_barrier
	s_waitcnt lgkmcnt(0)
	s_setprio 1
	v_mfma_f32_16x16x32_bf16 v[62:65], v[168:171], v[184:187], v[62:65]
	v_mfma_f32_16x16x32_bf16 v[50:53], v[176:179], v[184:187], v[50:53]
	v_mfma_f32_16x16x32_bf16 v[46:49], v[168:171], v[192:195], v[46:49]
	v_mfma_f32_16x16x32_bf16 v[34:37], v[176:179], v[192:195], v[34:37]
	v_mfma_f32_16x16x32_bf16 v[30:33], v[168:171], v[200:203], v[30:33]
	v_mfma_f32_16x16x32_bf16 v[18:21], v[176:179], v[200:203], v[18:21]
	v_mfma_f32_16x16x32_bf16 v[14:17], v[168:171], v[208:211], v[14:17]
	v_mfma_f32_16x16x32_bf16 v[6:9], v[176:179], v[208:211], v[6:9]
	v_mfma_f32_16x16x32_bf16 v[62:65], v[172:175], v[188:191], v[62:65]
	v_mfma_f32_16x16x32_bf16 v[50:53], v[180:183], v[188:191], v[50:53]
	v_mfma_f32_16x16x32_bf16 v[46:49], v[172:175], v[196:199], v[46:49]
	v_mfma_f32_16x16x32_bf16 v[34:37], v[180:183], v[196:199], v[34:37]
	v_mfma_f32_16x16x32_bf16 v[30:33], v[172:175], v[204:207], v[30:33]
	v_mfma_f32_16x16x32_bf16 v[18:21], v[180:183], v[204:207], v[18:21]
	v_mfma_f32_16x16x32_bf16 v[14:17], v[172:175], v[212:215], v[14:17]
	v_mfma_f32_16x16x32_bf16 v[6:9], v[180:183], v[212:215], v[6:9]
	s_setprio 0
	s_barrier
	s_add_u32 s68, s2, 0x40000
	s_addc_u32 s69, s3, 0
	s_add_i32 s70, s70, s98
	v_lshl_add_u64 v[162:163], s[68:69], 0, v[0:1]
	s_mov_b32 m0, s70
	s_nop 0
	global_load_lds_dwordx4 v[162:163], off
	v_lshl_add_u64 v[162:163], s[68:69], 0, v[144:145]
	s_add_i32 m0, s70, 0x2000
	s_nop 0
	global_load_lds_dwordx4 v[162:163], off
	s_waitcnt vmcnt(6)
	s_barrier
	s_setprio 1
	v_mfma_f32_16x16x32_bf16 v[58:61], v[216:219], v[184:187], v[58:61]
	v_mfma_f32_16x16x32_bf16 v[54:57], v[224:227], v[184:187], v[54:57]
	v_mfma_f32_16x16x32_bf16 v[42:45], v[216:219], v[192:195], v[42:45]
	v_mfma_f32_16x16x32_bf16 v[38:41], v[224:227], v[192:195], v[38:41]
	v_mfma_f32_16x16x32_bf16 v[26:29], v[216:219], v[200:203], v[26:29]
	v_mfma_f32_16x16x32_bf16 v[22:25], v[224:227], v[200:203], v[22:25]
	v_mfma_f32_16x16x32_bf16 v[10:13], v[216:219], v[208:211], v[10:13]
	v_mfma_f32_16x16x32_bf16 v[2:5], v[224:227], v[208:211], v[2:5]
	v_mfma_f32_16x16x32_bf16 v[58:61], v[220:223], v[188:191], v[58:61]
	v_mfma_f32_16x16x32_bf16 v[54:57], v[228:231], v[188:191], v[54:57]
	v_mfma_f32_16x16x32_bf16 v[42:45], v[220:223], v[196:199], v[42:45]
	v_mfma_f32_16x16x32_bf16 v[38:41], v[228:231], v[196:199], v[38:41]
	v_mfma_f32_16x16x32_bf16 v[26:29], v[220:223], v[204:207], v[26:29]
	v_mfma_f32_16x16x32_bf16 v[22:25], v[228:231], v[204:207], v[22:25]
	v_mfma_f32_16x16x32_bf16 v[10:13], v[220:223], v[212:215], v[10:13]
	v_mfma_f32_16x16x32_bf16 v[2:5], v[228:231], v[212:215], v[2:5]
	s_setprio 0
	s_add_i32 s68, 0, 0x18000
	v_add_u32_e32 v162, s68, v143
	s_barrier
	ds_read_b128 v[168:171], v162
	ds_read_b128 v[172:175], v162 offset:1024
	ds_read_b128 v[176:179], v162 offset:2048
	ds_read_b128 v[180:183], v162 offset:3072
	s_add_u32 s28, s28, 0x40000
	s_addc_u32 s29, s29, 0
	s_mov_b32 m0, s96
	v_lshl_add_u64 v[162:163], s[28:29], 0, v[148:149]
	ds_read_b128 v[184:187], v157 offset:32768
	ds_read_b128 v[188:191], v157 offset:33792
	ds_read_b128 v[192:195], v157 offset:34816
	ds_read_b128 v[196:199], v157 offset:35840
	ds_read_b128 v[200:203], v157 offset:36864
	ds_read_b128 v[204:207], v157 offset:37888
	ds_read_b128 v[208:211], v157 offset:38912
	ds_read_b128 v[212:215], v157 offset:39936
	global_load_lds_dwordx4 v[162:163], off
	v_lshl_add_u64 v[162:163], s[28:29], 0, v[146:147]
	s_mov_b32 m0, s35
	s_nop 0
	global_load_lds_dwordx4 v[162:163], off
	s_waitcnt lgkmcnt(8)
	s_barrier
	s_waitcnt lgkmcnt(0)
	s_setprio 1
	v_mfma_f32_16x16x32_bf16 v[126:129], v[168:171], v[184:187], v[126:129]
	v_mfma_f32_16x16x32_bf16 v[114:117], v[176:179], v[184:187], v[114:117]
	v_mfma_f32_16x16x32_bf16 v[110:113], v[168:171], v[192:195], v[110:113]
	v_mfma_f32_16x16x32_bf16 v[98:101], v[176:179], v[192:195], v[98:101]
	v_mfma_f32_16x16x32_bf16 v[94:97], v[168:171], v[200:203], v[94:97]
	v_mfma_f32_16x16x32_bf16 v[82:85], v[176:179], v[200:203], v[82:85]
	v_mfma_f32_16x16x32_bf16 v[78:81], v[168:171], v[208:211], v[78:81]
	v_mfma_f32_16x16x32_bf16 v[66:69], v[176:179], v[208:211], v[66:69]
	v_mfma_f32_16x16x32_bf16 v[126:129], v[172:175], v[188:191], v[126:129]
	v_mfma_f32_16x16x32_bf16 v[114:117], v[180:183], v[188:191], v[114:117]
	v_mfma_f32_16x16x32_bf16 v[110:113], v[172:175], v[196:199], v[110:113]
	v_mfma_f32_16x16x32_bf16 v[98:101], v[180:183], v[196:199], v[98:101]
	v_mfma_f32_16x16x32_bf16 v[94:97], v[172:175], v[204:207], v[94:97]
	v_mfma_f32_16x16x32_bf16 v[82:85], v[180:183], v[204:207], v[82:85]
	v_mfma_f32_16x16x32_bf16 v[78:81], v[172:175], v[212:215], v[78:81]
	v_mfma_f32_16x16x32_bf16 v[66:69], v[180:183], v[212:215], v[66:69]
	s_setprio 0
	s_barrier
	s_add_i32 s28, 0, 0x1c000
	s_add_i32 s29, s68, s98
	v_add_u32_e32 v162, s28, v143
	v_lshl_add_u64 v[130:131], v[130:131], 0, s[26:27]
	s_mov_b32 m0, s29
	ds_read_b128 v[216:219], v162
	ds_read_b128 v[220:223], v162 offset:1024
	ds_read_b128 v[224:227], v162 offset:2048
	ds_read_b128 v[228:231], v162 offset:3072
	global_load_lds_dwordx4 v[130:131], off
	v_lshl_add_u64 v[130:131], v[132:133], 0, s[26:27]
	s_add_i32 m0, s29, 0x2000
	s_nop 0
	global_load_lds_dwordx4 v[130:131], off
	s_barrier
	s_waitcnt lgkmcnt(0)
	s_setprio 1
	v_mfma_f32_16x16x32_bf16 v[122:125], v[216:219], v[184:187], v[122:125]
	v_mfma_f32_16x16x32_bf16 v[118:121], v[224:227], v[184:187], v[118:121]
	v_mfma_f32_16x16x32_bf16 v[106:109], v[216:219], v[192:195], v[106:109]
	v_mfma_f32_16x16x32_bf16 v[102:105], v[224:227], v[192:195], v[102:105]
	v_mfma_f32_16x16x32_bf16 v[90:93], v[216:219], v[200:203], v[90:93]
	v_mfma_f32_16x16x32_bf16 v[86:89], v[224:227], v[200:203], v[86:89]
	v_mfma_f32_16x16x32_bf16 v[74:77], v[216:219], v[208:211], v[74:77]
	v_mfma_f32_16x16x32_bf16 v[70:73], v[224:227], v[208:211], v[70:73]
	v_mfma_f32_16x16x32_bf16 v[122:125], v[220:223], v[188:191], v[122:125]
	v_mfma_f32_16x16x32_bf16 v[118:121], v[228:231], v[188:191], v[118:121]
	v_mfma_f32_16x16x32_bf16 v[106:109], v[220:223], v[196:199], v[106:109]
	v_mfma_f32_16x16x32_bf16 v[102:105], v[228:231], v[196:199], v[102:105]
	v_mfma_f32_16x16x32_bf16 v[90:93], v[220:223], v[204:207], v[90:93]
	v_mfma_f32_16x16x32_bf16 v[86:89], v[228:231], v[204:207], v[86:89]
	v_mfma_f32_16x16x32_bf16 v[74:77], v[220:223], v[212:215], v[74:77]
	v_mfma_f32_16x16x32_bf16 v[70:73], v[228:231], v[212:215], v[70:73]
	s_setprio 0
	s_mov_b32 m0, s33
	v_lshl_add_u64 v[130:131], v[154:155], 0, s[26:27]
	s_barrier
	ds_read_b128 v[184:187], v157 offset:49152
	ds_read_b128 v[188:191], v157 offset:50176
	ds_read_b128 v[192:195], v157 offset:51200
	ds_read_b128 v[196:199], v157 offset:52224
	ds_read_b128 v[200:203], v157 offset:53248
	ds_read_b128 v[204:207], v157 offset:54272
	ds_read_b128 v[208:211], v157 offset:55296
	ds_read_b128 v[212:215], v157 offset:56320
	global_load_lds_dwordx4 v[130:131], off
	v_lshl_add_u64 v[130:131], v[158:159], 0, s[26:27]
	s_mov_b32 m0, s44
	s_nop 0
	global_load_lds_dwordx4 v[130:131], off
	s_barrier
	s_waitcnt lgkmcnt(0)
	s_setprio 1
	v_mfma_f32_16x16x32_bf16 v[62:65], v[168:171], v[184:187], v[62:65]
	v_mfma_f32_16x16x32_bf16 v[50:53], v[176:179], v[184:187], v[50:53]
	v_mfma_f32_16x16x32_bf16 v[46:49], v[168:171], v[192:195], v[46:49]
	v_mfma_f32_16x16x32_bf16 v[34:37], v[176:179], v[192:195], v[34:37]
	v_mfma_f32_16x16x32_bf16 v[30:33], v[168:171], v[200:203], v[30:33]
	v_mfma_f32_16x16x32_bf16 v[18:21], v[176:179], v[200:203], v[18:21]
	v_mfma_f32_16x16x32_bf16 v[14:17], v[168:171], v[208:211], v[14:17]
	v_mfma_f32_16x16x32_bf16 v[6:9], v[176:179], v[208:211], v[6:9]
	v_mfma_f32_16x16x32_bf16 v[62:65], v[172:175], v[188:191], v[62:65]
	v_mfma_f32_16x16x32_bf16 v[50:53], v[180:183], v[188:191], v[50:53]
	v_mfma_f32_16x16x32_bf16 v[46:49], v[172:175], v[196:199], v[46:49]
	v_mfma_f32_16x16x32_bf16 v[34:37], v[180:183], v[196:199], v[34:37]
	v_mfma_f32_16x16x32_bf16 v[30:33], v[172:175], v[204:207], v[30:33]
	v_mfma_f32_16x16x32_bf16 v[18:21], v[180:183], v[204:207], v[18:21]
	v_mfma_f32_16x16x32_bf16 v[14:17], v[172:175], v[212:215], v[14:17]
	v_mfma_f32_16x16x32_bf16 v[6:9], v[180:183], v[212:215], v[6:9]
	s_setprio 0
	s_barrier
	s_add_u32 s2, s2, 0x40080
	s_addc_u32 s3, s3, 0
	s_add_i32 s28, s28, s98
	v_lshl_add_u64 v[130:131], s[2:3], 0, v[0:1]
	s_mov_b32 m0, s28
	s_nop 0
	global_load_lds_dwordx4 v[130:131], off
	v_lshl_add_u64 v[130:131], s[2:3], 0, v[144:145]
	s_add_i32 m0, s28, 0x2000
	s_nop 0
	global_load_lds_dwordx4 v[130:131], off
	s_waitcnt vmcnt(6)
	s_barrier
	s_setprio 1
	v_mfma_f32_16x16x32_bf16 v[58:61], v[216:219], v[184:187], v[58:61]
	v_mfma_f32_16x16x32_bf16 v[54:57], v[224:227], v[184:187], v[54:57]
	v_mfma_f32_16x16x32_bf16 v[42:45], v[216:219], v[192:195], v[42:45]
	v_mfma_f32_16x16x32_bf16 v[38:41], v[224:227], v[192:195], v[38:41]
	v_mfma_f32_16x16x32_bf16 v[26:29], v[216:219], v[200:203], v[26:29]
	v_mfma_f32_16x16x32_bf16 v[22:25], v[224:227], v[200:203], v[22:25]
	v_mfma_f32_16x16x32_bf16 v[10:13], v[216:219], v[208:211], v[10:13]
	v_mfma_f32_16x16x32_bf16 v[2:5], v[224:227], v[208:211], v[2:5]
	v_mfma_f32_16x16x32_bf16 v[58:61], v[220:223], v[188:191], v[58:61]
	v_mfma_f32_16x16x32_bf16 v[54:57], v[228:231], v[188:191], v[54:57]
	v_mfma_f32_16x16x32_bf16 v[42:45], v[220:223], v[196:199], v[42:45]
	v_mfma_f32_16x16x32_bf16 v[38:41], v[228:231], v[196:199], v[38:41]
	v_mfma_f32_16x16x32_bf16 v[26:29], v[220:223], v[204:207], v[26:29]
	v_mfma_f32_16x16x32_bf16 v[22:25], v[228:231], v[204:207], v[22:25]
	v_mfma_f32_16x16x32_bf16 v[10:13], v[220:223], v[212:215], v[10:13]
	v_mfma_f32_16x16x32_bf16 v[2:5], v[228:231], v[212:215], v[2:5]
	s_setprio 0
	s_add_i32 s67, s67, 2
	s_add_u32 s20, s20, 0x100
	s_addc_u32 s21, s21, 0
	s_add_u32 s65, s65, 0x100
	s_addc_u32 s66, s66, 0
	s_cmp_gt_u32 s67, 13
	s_barrier
	s_cbranch_scc0 .LBB0_437
	s_andn2_b64 vcc, exec, s[0:1]
	s_cbranch_vccnz .LBB0_429
	v_pk_mul_f32 v[162:163], v[126:127], s[34:35] op_sel_hi:[1,0]
	v_pk_mul_f32 v[122:123], v[122:123], v[126:127]
	v_pk_mul_f32 v[126:127], v[128:129], s[34:35] op_sel_hi:[1,0]
	v_exp_f32_e32 v162, v162
	v_exp_f32_e32 v163, v163
	v_exp_f32_e32 v126, v126
	v_exp_f32_e32 v127, v127
	v_pk_mul_f32 v[124:125], v[124:125], v[128:129]
	v_pk_add_f32 v[162:163], v[162:163], 1.0 op_sel_hi:[1,0]
	v_pk_mul_f32 v[106:107], v[106:107], v[110:111]
	v_pk_add_f32 v[126:127], v[126:127], 1.0 op_sel_hi:[1,0]
	v_rcp_f32_e32 v162, v162
	v_rcp_f32_e32 v163, v163
	v_rcp_f32_e32 v126, v126
	v_rcp_f32_e32 v127, v127
	v_lshl_or_b32 v130, s40, 7, v156
	v_pk_mul_f32 v[122:123], v[122:123], v[162:163]
	v_pk_mul_f32 v[120:121], v[120:121], v[116:117]
	v_pk_mul_f32 v[124:125], v[124:125], v[126:127]
	v_cvt_pk_bf16_f32 v122, v122, v123
	v_lshl_add_u32 v158, s64, 8, v141
	v_cvt_pk_bf16_f32 v123, v124, v125
	v_pk_mul_f32 v[124:125], v[114:115], s[34:35] op_sel_hi:[1,0]
	v_pk_mul_f32 v[114:115], v[118:119], v[114:115]
	v_exp_f32_e32 v124, v124
	v_exp_f32_e32 v125, v125
	v_pk_mul_f32 v[118:119], v[110:111], s[34:35] op_sel_hi:[1,0]
	v_pk_mul_f32 v[110:111], v[112:113], s[34:35] op_sel_hi:[1,0]
	v_exp_f32_e32 v118, v118
	v_pk_add_f32 v[124:125], v[124:125], 1.0 op_sel_hi:[1,0]
	v_exp_f32_e32 v119, v119
	v_rcp_f32_e32 v124, v124
	v_rcp_f32_e32 v125, v125
	v_exp_f32_e32 v110, v110
	v_exp_f32_e32 v111, v111
	v_pk_add_f32 v[118:119], v[118:119], 1.0 op_sel_hi:[1,0]
	v_pk_mul_f32 v[114:115], v[114:115], v[124:125]
	v_rcp_f32_e32 v118, v118
	v_cvt_pk_bf16_f32 v124, v114, v115
	v_pk_mul_f32 v[114:115], v[116:117], s[34:35] op_sel_hi:[1,0]
	v_pk_add_f32 v[110:111], v[110:111], 1.0 op_sel_hi:[1,0]
	v_exp_f32_e32 v114, v114
	v_exp_f32_e32 v115, v115
	v_rcp_f32_e32 v119, v119
	v_rcp_f32_e32 v110, v110
	v_rcp_f32_e32 v111, v111
	v_pk_add_f32 v[114:115], v[114:115], 1.0 op_sel_hi:[1,0]
	v_ashrrev_i32_e32 v131, 31, v130
	v_rcp_f32_e32 v114, v114
	v_rcp_f32_e32 v115, v115
	v_mov_b64_e32 v[154:155], s[62:63]
	s_movk_i32 s20, 0x1600
	v_mad_i64_i32 v[132:133], s[2:3], v158, s20, v[154:155]
	v_pk_mul_f32 v[114:115], v[120:121], v[114:115]
	v_pk_mul_f32 v[108:109], v[108:109], v[112:113]
	v_cvt_pk_bf16_f32 v125, v114, v115
	v_lshlrev_b64 v[114:115], 1, v[130:131]
	v_lshl_add_u64 v[116:117], v[132:133], 0, v[114:115]
	v_pk_mul_f32 v[106:107], v[106:107], v[118:119]
	v_pk_mul_f32 v[108:109], v[108:109], v[110:111]
	global_store_dwordx4 v[116:117], v[122:125], off
	v_cvt_pk_bf16_f32 v106, v106, v107
	v_cvt_pk_bf16_f32 v107, v108, v109
	v_pk_mul_f32 v[108:109], v[98:99], s[34:35] op_sel_hi:[1,0]
	v_pk_mul_f32 v[98:99], v[102:103], v[98:99]
	v_exp_f32_e32 v108, v108
	v_exp_f32_e32 v109, v109
	v_pk_mul_f32 v[104:105], v[104:105], v[100:101]
	v_pk_mul_f32 v[90:91], v[90:91], v[94:95]
	v_or_b32_e32 v116, 16, v158
	v_pk_add_f32 v[108:109], v[108:109], 1.0 op_sel_hi:[1,0]
	v_mad_i64_i32 v[116:117], s[2:3], v116, s20, v[154:155]
	v_rcp_f32_e32 v108, v108
	v_rcp_f32_e32 v109, v109
	v_pk_mul_f32 v[92:93], v[92:93], v[96:97]
	v_pk_mul_f32 v[88:89], v[88:89], v[84:85]
	v_pk_mul_f32 v[74:75], v[74:75], v[78:79]
	v_pk_mul_f32 v[98:99], v[98:99], v[108:109]
	v_pk_mul_f32 v[76:77], v[76:77], v[80:81]
	v_cvt_pk_bf16_f32 v108, v98, v99
	v_pk_mul_f32 v[98:99], v[100:101], s[34:35] op_sel_hi:[1,0]
	v_pk_mul_f32 v[100:101], v[94:95], s[34:35] op_sel_hi:[1,0]
	v_exp_f32_e32 v98, v98
	v_exp_f32_e32 v99, v99
	v_pk_mul_f32 v[94:95], v[96:97], s[34:35] op_sel_hi:[1,0]
	v_exp_f32_e32 v100, v100
	v_exp_f32_e32 v101, v101
	v_exp_f32_e32 v94, v94
	v_exp_f32_e32 v95, v95
	v_pk_add_f32 v[98:99], v[98:99], 1.0 op_sel_hi:[1,0]
	v_pk_add_f32 v[100:101], v[100:101], 1.0 op_sel_hi:[1,0]
	v_rcp_f32_e32 v98, v98
	v_rcp_f32_e32 v99, v99
	v_pk_add_f32 v[94:95], v[94:95], 1.0 op_sel_hi:[1,0]
	v_rcp_f32_e32 v100, v100
	v_rcp_f32_e32 v101, v101
	v_rcp_f32_e32 v94, v94
	v_rcp_f32_e32 v95, v95
	v_pk_mul_f32 v[98:99], v[104:105], v[98:99]
	v_pk_mul_f32 v[90:91], v[90:91], v[100:101]
	v_cvt_pk_bf16_f32 v109, v98, v99
	v_lshl_add_u64 v[98:99], v[116:117], 0, v[114:115]
	v_pk_mul_f32 v[92:93], v[92:93], v[94:95]
	global_store_dwordx4 v[98:99], v[106:109], off
	v_cvt_pk_bf16_f32 v90, v90, v91
	v_cvt_pk_bf16_f32 v91, v92, v93
	v_pk_mul_f32 v[92:93], v[82:83], s[34:35] op_sel_hi:[1,0]
	v_pk_mul_f32 v[82:83], v[86:87], v[82:83]
	v_exp_f32_e32 v92, v92
	v_exp_f32_e32 v93, v93
	v_or_b32_e32 v98, 32, v158
	v_mad_i64_i32 v[98:99], s[2:3], v98, s20, v[154:155]
	v_pk_add_f32 v[92:93], v[92:93], 1.0 op_sel_hi:[1,0]
	v_pk_mul_f32 v[72:73], v[72:73], v[68:69]
	v_rcp_f32_e32 v92, v92
	v_rcp_f32_e32 v93, v93
	v_pk_mul_f32 v[58:59], v[58:59], v[62:63]
	v_pk_mul_f32 v[60:61], v[60:61], v[64:65]
	v_pk_mul_f32 v[56:57], v[56:57], v[52:53]
	v_pk_mul_f32 v[82:83], v[82:83], v[92:93]
	v_pk_mul_f32 v[42:43], v[42:43], v[46:47]
	v_cvt_pk_bf16_f32 v92, v82, v83
	v_pk_mul_f32 v[82:83], v[84:85], s[34:35] op_sel_hi:[1,0]
	v_pk_mul_f32 v[84:85], v[78:79], s[34:35] op_sel_hi:[1,0]
	v_exp_f32_e32 v82, v82
	v_exp_f32_e32 v83, v83
	v_pk_mul_f32 v[78:79], v[80:81], s[34:35] op_sel_hi:[1,0]
	v_exp_f32_e32 v84, v84
	v_exp_f32_e32 v85, v85
	v_exp_f32_e32 v78, v78
	v_exp_f32_e32 v79, v79
	v_pk_add_f32 v[82:83], v[82:83], 1.0 op_sel_hi:[1,0]
	v_pk_add_f32 v[84:85], v[84:85], 1.0 op_sel_hi:[1,0]
	v_rcp_f32_e32 v82, v82
	v_rcp_f32_e32 v83, v83
	v_pk_add_f32 v[78:79], v[78:79], 1.0 op_sel_hi:[1,0]
	v_rcp_f32_e32 v84, v84
	v_rcp_f32_e32 v85, v85
	v_rcp_f32_e32 v78, v78
	v_rcp_f32_e32 v79, v79
	v_pk_mul_f32 v[82:83], v[88:89], v[82:83]
	v_pk_mul_f32 v[74:75], v[74:75], v[84:85]
	v_cvt_pk_bf16_f32 v93, v82, v83
	v_lshl_add_u64 v[82:83], v[98:99], 0, v[114:115]
	v_pk_mul_f32 v[76:77], v[76:77], v[78:79]
	global_store_dwordx4 v[82:83], v[90:93], off
	v_cvt_pk_bf16_f32 v74, v74, v75
	v_cvt_pk_bf16_f32 v75, v76, v77
	v_pk_mul_f32 v[76:77], v[66:67], s[34:35] op_sel_hi:[1,0]
	v_pk_mul_f32 v[66:67], v[70:71], v[66:67]
	v_exp_f32_e32 v76, v76
	v_exp_f32_e32 v77, v77
	v_or_b32_e32 v82, 48, v158
	v_mad_i64_i32 v[82:83], s[2:3], v82, s20, v[154:155]
	v_pk_add_f32 v[76:77], v[76:77], 1.0 op_sel_hi:[1,0]
	v_pk_mul_f32 v[44:45], v[44:45], v[48:49]
	v_rcp_f32_e32 v76, v76
	v_rcp_f32_e32 v77, v77
	v_pk_mul_f32 v[40:41], v[40:41], v[36:37]
	v_pk_mul_f32 v[26:27], v[26:27], v[30:31]
	v_pk_mul_f32 v[28:29], v[28:29], v[32:33]
	v_pk_mul_f32 v[66:67], v[66:67], v[76:77]
	v_pk_mul_f32 v[24:25], v[24:25], v[20:21]
	v_cvt_pk_bf16_f32 v76, v66, v67
	v_pk_mul_f32 v[66:67], v[68:69], s[34:35] op_sel_hi:[1,0]
	v_pk_mul_f32 v[68:69], v[62:63], s[34:35] op_sel_hi:[1,0]
	v_exp_f32_e32 v66, v66
	v_exp_f32_e32 v67, v67
	v_pk_mul_f32 v[62:63], v[64:65], s[34:35] op_sel_hi:[1,0]
	v_exp_f32_e32 v68, v68
	v_exp_f32_e32 v69, v69
	v_exp_f32_e32 v62, v62
	v_exp_f32_e32 v63, v63
	v_pk_add_f32 v[66:67], v[66:67], 1.0 op_sel_hi:[1,0]
	v_pk_add_f32 v[68:69], v[68:69], 1.0 op_sel_hi:[1,0]
	v_rcp_f32_e32 v66, v66
	v_rcp_f32_e32 v67, v67
	v_pk_add_f32 v[62:63], v[62:63], 1.0 op_sel_hi:[1,0]
	v_rcp_f32_e32 v68, v68
	v_rcp_f32_e32 v69, v69
	v_rcp_f32_e32 v62, v62
	v_rcp_f32_e32 v63, v63
	v_pk_mul_f32 v[66:67], v[72:73], v[66:67]
	v_pk_mul_f32 v[58:59], v[58:59], v[68:69]
	v_cvt_pk_bf16_f32 v77, v66, v67
	v_lshl_add_u64 v[66:67], v[82:83], 0, v[114:115]
	v_pk_mul_f32 v[60:61], v[60:61], v[62:63]
	global_store_dwordx4 v[66:67], v[74:77], off
	v_cvt_pk_bf16_f32 v58, v58, v59
	v_cvt_pk_bf16_f32 v59, v60, v61
	v_pk_mul_f32 v[60:61], v[50:51], s[34:35] op_sel_hi:[1,0]
	v_pk_mul_f32 v[50:51], v[54:55], v[50:51]
	v_exp_f32_e32 v60, v60
	v_exp_f32_e32 v61, v61
	v_add_u32_e32 v66, 0x80, v158
	v_mad_i64_i32 v[66:67], s[2:3], v66, s20, v[154:155]
	v_pk_add_f32 v[60:61], v[60:61], 1.0 op_sel_hi:[1,0]
	v_pk_mul_f32 v[10:11], v[10:11], v[14:15]
	v_rcp_f32_e32 v60, v60
	v_rcp_f32_e32 v61, v61
	v_pk_mul_f32 v[12:13], v[12:13], v[16:17]
	v_pk_mul_f32 v[2:3], v[2:3], v[6:7]
	v_pk_mul_f32 v[4:5], v[4:5], v[8:9]
	v_pk_mul_f32 v[50:51], v[50:51], v[60:61]
	s_nop 0
	v_cvt_pk_bf16_f32 v60, v50, v51
	v_pk_mul_f32 v[50:51], v[52:53], s[34:35] op_sel_hi:[1,0]
	v_pk_mul_f32 v[52:53], v[46:47], s[34:35] op_sel_hi:[1,0]
	v_exp_f32_e32 v50, v50
	v_exp_f32_e32 v51, v51
	v_pk_mul_f32 v[46:47], v[48:49], s[34:35] op_sel_hi:[1,0]
	v_exp_f32_e32 v52, v52
	v_exp_f32_e32 v53, v53
	v_exp_f32_e32 v46, v46
	v_exp_f32_e32 v47, v47
	v_pk_add_f32 v[50:51], v[50:51], 1.0 op_sel_hi:[1,0]
	v_pk_add_f32 v[52:53], v[52:53], 1.0 op_sel_hi:[1,0]
	v_rcp_f32_e32 v50, v50
	v_rcp_f32_e32 v51, v51
	v_pk_add_f32 v[46:47], v[46:47], 1.0 op_sel_hi:[1,0]
	v_rcp_f32_e32 v52, v52
	v_rcp_f32_e32 v53, v53
	v_rcp_f32_e32 v46, v46
	v_rcp_f32_e32 v47, v47
	v_pk_mul_f32 v[50:51], v[56:57], v[50:51]
	v_pk_mul_f32 v[42:43], v[42:43], v[52:53]
	v_cvt_pk_bf16_f32 v61, v50, v51
	v_lshl_add_u64 v[50:51], v[66:67], 0, v[114:115]
	v_pk_mul_f32 v[44:45], v[44:45], v[46:47]
	global_store_dwordx4 v[50:51], v[58:61], off
	v_cvt_pk_bf16_f32 v42, v42, v43
	v_cvt_pk_bf16_f32 v43, v44, v45
	v_pk_mul_f32 v[44:45], v[34:35], s[34:35] op_sel_hi:[1,0]
	v_pk_mul_f32 v[34:35], v[38:39], v[34:35]
	v_exp_f32_e32 v44, v44
	v_exp_f32_e32 v45, v45
	v_add_u32_e32 v50, 0x90, v158
	v_mad_i64_i32 v[50:51], s[2:3], v50, s20, v[154:155]
	v_pk_add_f32 v[44:45], v[44:45], 1.0 op_sel_hi:[1,0]
	s_nop 0
	v_rcp_f32_e32 v44, v44
	v_rcp_f32_e32 v45, v45
	s_nop 0
	v_pk_mul_f32 v[34:35], v[34:35], v[44:45]
	s_nop 0
	v_cvt_pk_bf16_f32 v44, v34, v35
	v_pk_mul_f32 v[34:35], v[36:37], s[34:35] op_sel_hi:[1,0]
	v_pk_mul_f32 v[36:37], v[30:31], s[34:35] op_sel_hi:[1,0]
	v_exp_f32_e32 v34, v34
	v_exp_f32_e32 v35, v35
	v_pk_mul_f32 v[30:31], v[32:33], s[34:35] op_sel_hi:[1,0]
	v_exp_f32_e32 v36, v36
	v_exp_f32_e32 v37, v37
	v_exp_f32_e32 v30, v30
	v_exp_f32_e32 v31, v31
	v_pk_add_f32 v[34:35], v[34:35], 1.0 op_sel_hi:[1,0]
	v_pk_add_f32 v[36:37], v[36:37], 1.0 op_sel_hi:[1,0]
	v_rcp_f32_e32 v34, v34
	v_rcp_f32_e32 v35, v35
	v_pk_add_f32 v[30:31], v[30:31], 1.0 op_sel_hi:[1,0]
	v_rcp_f32_e32 v36, v36
	v_rcp_f32_e32 v37, v37
	v_rcp_f32_e32 v30, v30
	v_rcp_f32_e32 v31, v31
	v_pk_mul_f32 v[34:35], v[40:41], v[34:35]
	v_pk_mul_f32 v[26:27], v[26:27], v[36:37]
	v_cvt_pk_bf16_f32 v45, v34, v35
	v_lshl_add_u64 v[34:35], v[50:51], 0, v[114:115]
	v_pk_mul_f32 v[28:29], v[28:29], v[30:31]
	global_store_dwordx4 v[34:35], v[42:45], off
	v_cvt_pk_bf16_f32 v26, v26, v27
	v_cvt_pk_bf16_f32 v27, v28, v29
	v_pk_mul_f32 v[28:29], v[18:19], s[34:35] op_sel_hi:[1,0]
	v_pk_mul_f32 v[18:19], v[22:23], v[18:19]
	v_exp_f32_e32 v28, v28
	v_exp_f32_e32 v29, v29
	v_add_u32_e32 v34, 0xa0, v158
	v_mad_i64_i32 v[34:35], s[2:3], v34, s20, v[154:155]
	v_pk_add_f32 v[28:29], v[28:29], 1.0 op_sel_hi:[1,0]
	s_nop 0
	v_rcp_f32_e32 v28, v28
	v_rcp_f32_e32 v29, v29
	s_nop 0
	v_pk_mul_f32 v[18:19], v[18:19], v[28:29]
	s_nop 0
	v_cvt_pk_bf16_f32 v28, v18, v19
	v_pk_mul_f32 v[18:19], v[20:21], s[34:35] op_sel_hi:[1,0]
	v_pk_mul_f32 v[20:21], v[14:15], s[34:35] op_sel_hi:[1,0]
	v_exp_f32_e32 v18, v18
	v_exp_f32_e32 v19, v19
	v_pk_mul_f32 v[14:15], v[16:17], s[34:35] op_sel_hi:[1,0]
	v_exp_f32_e32 v20, v20
	v_exp_f32_e32 v21, v21
	v_exp_f32_e32 v14, v14
	v_exp_f32_e32 v15, v15
	v_pk_add_f32 v[18:19], v[18:19], 1.0 op_sel_hi:[1,0]
	v_pk_add_f32 v[20:21], v[20:21], 1.0 op_sel_hi:[1,0]
	v_rcp_f32_e32 v18, v18
	v_rcp_f32_e32 v19, v19
	v_pk_add_f32 v[14:15], v[14:15], 1.0 op_sel_hi:[1,0]
	v_rcp_f32_e32 v20, v20
	v_rcp_f32_e32 v21, v21
	v_rcp_f32_e32 v14, v14
	v_rcp_f32_e32 v15, v15
	v_pk_mul_f32 v[18:19], v[24:25], v[18:19]
	v_pk_mul_f32 v[10:11], v[10:11], v[20:21]
	v_cvt_pk_bf16_f32 v29, v18, v19
	v_lshl_add_u64 v[18:19], v[34:35], 0, v[114:115]
	v_pk_mul_f32 v[12:13], v[12:13], v[14:15]
	global_store_dwordx4 v[18:19], v[26:29], off
	v_cvt_pk_bf16_f32 v10, v10, v11
	v_cvt_pk_bf16_f32 v11, v12, v13
	v_pk_mul_f32 v[12:13], v[6:7], s[34:35] op_sel_hi:[1,0]
	v_add_u32_e32 v18, 0xb0, v158
	v_exp_f32_e32 v12, v12
	v_exp_f32_e32 v13, v13
	v_mad_i64_i32 v[18:19], s[2:3], v18, s20, v[154:155]
	v_pk_add_f32 v[12:13], v[12:13], 1.0 op_sel_hi:[1,0]
	s_nop 0
	v_rcp_f32_e32 v12, v12
	v_rcp_f32_e32 v13, v13
	s_nop 0
	v_pk_mul_f32 v[2:3], v[2:3], v[12:13]
	s_nop 0
	v_cvt_pk_bf16_f32 v12, v2, v3
	v_pk_mul_f32 v[2:3], v[8:9], s[34:35] op_sel_hi:[1,0]
	s_nop 0
	v_exp_f32_e32 v2, v2
	v_exp_f32_e32 v3, v3
	s_nop 0
	v_pk_add_f32 v[2:3], v[2:3], 1.0 op_sel_hi:[1,0]
	s_nop 0
	v_rcp_f32_e32 v2, v2
	v_rcp_f32_e32 v3, v3
	s_nop 0
	v_pk_mul_f32 v[2:3], v[4:5], v[2:3]
	s_nop 0
	v_cvt_pk_bf16_f32 v13, v2, v3
	v_lshl_add_u64 v[2:3], v[18:19], 0, v[114:115]
	global_store_dwordx4 v[2:3], v[10:13], off
	s_branch .LBB0_429
